# diff table-biased tiles: bias read straight into the QK accumulators (raw units), one softmax front for table and constant-bias tiles (no separate fma+sub path)
# baseline (speedup 1.0000x reference)
; DI void diff_item(const Params& P, char* lds, int layer, int pair, int qt, int& tab_head) {
;     ...
;     float* ctab = (float*)(lds + LDS_CTAB);
;     const float* tabg = (const float*)(P.ws + WS_TABC) + head * 2112;
;     if (tab_head != head) { for (int i = tid; i < 2112; i += NTHR) ctab[i] = tabg[i]; tab_head = head; }
.LBB0_248:
	flat_load_dword v6, v[2:3]
	v_add_u32_e32 v0, 0x200, v0
	s_movk_i32 s16, 0x63f
	s_mov_b64 s[40:41], 0x800
	v_cmp_lt_i32_e32 vcc, s16, v0
	v_lshl_add_u64 v[2:3], v[2:3], 0, s[40:41]
	s_or_b64 s[22:23], vcc, s[22:23]
	s_waitcnt vmcnt(0) lgkmcnt(0)
	v_mul_f32_e32 v6, 0x40b17218, v6
	ds_write_b32 v5, v6
	v_add_u32_e32 v5, 0x800, v5
	s_andn2_b64 exec, exec, s[22:23]
	s_cbranch_execnz .LBB0_248
	s_or_b64 exec, exec, s[22:23]

; #define LAS __attribute__((address_space(3)))
; #define MFMA(a, b, c) __builtin_amdgcn_mfma_f32_32x32x16_bf16((a), (b), (c), 0, 0, 0)
; template <typename F>
; DI void diff_step(lptr sK, lptr sV, int kx0, int vl0, const bf16x8 (&qf)[4], float& m, float& l, f32x16 (&O)[4],
;                   const LAS float* tb, bool far, float cfar, int lane, F&& mid) {
;     ...
;     lptr kr = sK + r * 256;
;     bf16x8 kf[8];
; #pragma unroll
;     for (int s = 0; s < 4; ++s) {
;         const int co = (kx0 ^ (2 * s)) * 16;
;         kf[2 * s] = *(const LAS bf16x8*)(kr + co);
;         kf[2 * s + 1] = *(const LAS bf16x8*)(kr + 8192 + co);
;     }
;     __builtin_amdgcn_sched_barrier(0);
;     mid();
;     __builtin_amdgcn_sched_barrier(0);
; #pragma unroll
;     for (int s = 0; s < 4; ++s) { p0 = MFMA(kf[2 * s], qf[s], p0); p1 = MFMA(kf[2 * s + 1], qf[s], p1); }
.Ldu_A:
	s_waitcnt vmcnt(0)
	s_waitcnt lgkmcnt(0)
	s_barrier
	v_cmp_gt_i32_e64 s[100:101], s42, v217
	ds_read_b128 v[248:251], v14
	ds_read_b128 v[252:255], v14 offset:8192
	ds_read_b128 v[120:123], v15
	ds_read_b128 v[6:9], v15 offset:8192
	ds_read_b128 v[116:119], v221
	ds_read_b128 v[2:5], v221 offset:8192
	ds_read_b128 v[10:13], v222
	ds_read_b128 v[112:115], v222 offset:8192
	v_add_u32_e32 v220, 1, v220
	s_add_u32 s72, s63, 0x8000
	s_mov_b32 m0, s72
	s_nop 0
	global_load_lds_dwordx4 v170, s[64:65]
	s_add_u32 s72, s63, 0xc000
	s_mov_b32 m0, s72
	s_nop 0
	global_load_lds_dwordx4 v170, s[70:71]
	s_add_u32 s72, s63, 0x8400
	s_mov_b32 m0, s72
	s_nop 0
	global_load_lds_dwordx4 v172, s[64:65]
	s_add_u32 s72, s63, 0xc400
	s_mov_b32 m0, s72
	s_nop 0
	global_load_lds_dwordx4 v172, s[70:71]
	s_add_u32 s64, s64, 0xe0000
	s_addc_u32 s65, s65, 0
	s_add_u32 s70, s70, 0xe0000
	s_addc_u32 s71, s71, 0
	s_cmp_eq_u64 s[100:101], 0
	s_cbranch_scc1 .Lqk_far_a
	ds_read2_b32 v[96:97], v218 offset0:59 offset1:58
	ds_read2_b32 v[98:99], v218 offset0:57 offset1:56
	ds_read2_b32 v[100:101], v218 offset0:51 offset1:50
	ds_read2_b32 v[102:103], v218 offset0:49 offset1:48
	ds_read2_b32 v[104:105], v218 offset0:43 offset1:42
	ds_read2_b32 v[106:107], v218 offset0:41 offset1:40
	ds_read2_b32 v[108:109], v218 offset0:35 offset1:34
	ds_read2_b32 v[110:111], v218 offset0:33 offset1:32
	ds_read2_b32 v[80:81], v218 offset0:27 offset1:26
	ds_read2_b32 v[82:83], v218 offset0:25 offset1:24
	ds_read2_b32 v[84:85], v218 offset0:19 offset1:18
	ds_read2_b32 v[86:87], v218 offset0:17 offset1:16
	ds_read2_b32 v[88:89], v218 offset0:11 offset1:10
	ds_read2_b32 v[90:91], v218 offset0:9 offset1:8
	ds_read2_b32 v[92:93], v218 offset0:3 offset1:2
	ds_read2_b32 v[94:95], v218 offset0:1 offset1:0
	v_mov_b32_e32 v242, 0
	s_waitcnt lgkmcnt(0)
	v_mfma_f32_32x32x16_bf16 v[96:111], v[248:251], v[144:147], v[96:111]
	v_mfma_f32_32x32x16_bf16 v[80:95], v[252:255], v[144:147], v[80:95]
	s_branch .Lqk_join_a
.Lqk_far_a:
	v_mov_b32_e32 v242, v198
	s_waitcnt lgkmcnt(7)
	v_mfma_f32_32x32x16_bf16 v[96:111], v[248:251], v[144:147], 0
	s_waitcnt lgkmcnt(6)
	v_mfma_f32_32x32x16_bf16 v[80:95], v[252:255], v[144:147], 0
.Lqk_join_a:
	s_waitcnt lgkmcnt(5)
	v_mfma_f32_32x32x16_bf16 v[96:111], v[120:123], v[148:151], v[96:111]
	s_waitcnt lgkmcnt(4)
	v_mfma_f32_32x32x16_bf16 v[80:95], v[6:9], v[148:151], v[80:95]
	s_waitcnt lgkmcnt(3)
	v_mfma_f32_32x32x16_bf16 v[96:111], v[116:119], v[152:155], v[96:111]
	s_waitcnt lgkmcnt(2)
	v_mfma_f32_32x32x16_bf16 v[80:95], v[2:5], v[152:155], v[80:95]
	ds_read_b64_tr_b16 v[2:3], v199 offset:16384
	ds_read_b64_tr_b16 v[4:5], v210 offset:18432
	ds_read_b64_tr_b16 v[6:7], v211 offset:16384
	ds_read_b64_tr_b16 v[8:9], v212 offset:18432
	s_waitcnt lgkmcnt(5)
	v_mfma_f32_32x32x16_bf16 v[96:111], v[10:13], v[156:159], v[96:111]
	ds_read_b64_tr_b16 v[10:11], v213 offset:16384
	ds_read_b64_tr_b16 v[12:13], v214 offset:18432
	ds_read_b64_tr_b16 v[160:161], v215 offset:16384
	ds_read_b64_tr_b16 v[162:163], v216 offset:18432
	s_waitcnt lgkmcnt(8)
	v_mfma_f32_32x32x16_bf16 v[80:95], v[112:115], v[156:159], v[80:95]
	s_nop 7
	s_nop 7
	s_nop 3
	v_sub_f32_e32 v243, v242, v226
	v_max3_f32 v244, v96, v97, v80
	v_fma_f32 v112, v96, v178, v243
	v_fma_f32 v128, v80, v178, v243
	v_max3_f32 v245, v98, v99, v81
	v_fma_f32 v113, v97, v178, v243
	v_fma_f32 v129, v81, v178, v243
	v_max3_f32 v244, v244, v82, v83
	v_fma_f32 v114, v98, v178, v243
	v_fma_f32 v130, v82, v178, v243
	v_max3_f32 v245, v245, v102, v103
	v_fma_f32 v115, v99, v178, v243
	v_fma_f32 v131, v83, v178, v243
	v_max3_f32 v244, v244, v100, v101
	v_fma_f32 v116, v100, v178, v243
	v_fma_f32 v132, v84, v178, v243
	v_max3_f32 v245, v245, v86, v87
	v_fma_f32 v117, v101, v178, v243
	v_fma_f32 v133, v85, v178, v243
	v_max3_f32 v244, v244, v84, v85
	v_fma_f32 v118, v102, v178, v243
	v_fma_f32 v134, v86, v178, v243
	v_max3_f32 v245, v245, v106, v107
	v_fma_f32 v119, v103, v178, v243
	v_fma_f32 v135, v87, v178, v243
	v_max3_f32 v244, v244, v104, v105
	v_fma_f32 v120, v104, v178, v243
	v_fma_f32 v136, v88, v178, v243
	v_max3_f32 v245, v245, v90, v91
	v_fma_f32 v121, v105, v178, v243
	v_fma_f32 v137, v89, v178, v243
	v_max3_f32 v244, v244, v88, v89
	v_fma_f32 v122, v106, v178, v243
	v_fma_f32 v138, v90, v178, v243
	v_max3_f32 v245, v245, v110, v111
	v_fma_f32 v123, v107, v178, v243
	v_fma_f32 v139, v91, v178, v243
	v_max3_f32 v244, v244, v108, v109
	v_fma_f32 v124, v108, v178, v243
	v_fma_f32 v140, v92, v178, v243
	v_max3_f32 v245, v245, v94, v95
	v_fma_f32 v125, v109, v178, v243
	v_fma_f32 v141, v93, v178, v243
	v_max3_f32 v244, v244, v92, v93
	v_fma_f32 v126, v110, v178, v243
	v_fma_f32 v142, v94, v178, v243
	v_fma_f32 v127, v111, v178, v243
	v_fma_f32 v143, v95, v178, v243
	v_max_f32_e32 v244, v244, v245
	v_mov_b32_e32 v245, v244
	s_nop 1
	v_permlane32_swap_b32_e32 v244, v245
	v_max_f32_e32 v244, v244, v245
	v_fmamk_f32 v244, v244, 0x3e38aa3b, v242
	v_sub_f32_e32 v245, v244, v226
	v_cmp_lt_f32_e32 vcc, s45, v245
	v_max_f32_e32 v244, v226, v244
	s_nop 0
	v_cndmask_b32_e32 v227, v226, v244, vcc
	s_nop 2
	s_cbranch_vccz .Ldf_far_nofix_a
	v_sub_f32_e32 v243, v242, v227
	v_fma_f32 v112, v96, v178, v243
	v_fma_f32 v128, v80, v178, v243
	v_fma_f32 v113, v97, v178, v243
	v_fma_f32 v129, v81, v178, v243
	v_fma_f32 v114, v98, v178, v243
	v_fma_f32 v130, v82, v178, v243
	v_fma_f32 v115, v99, v178, v243
	v_fma_f32 v131, v83, v178, v243
	v_fma_f32 v116, v100, v178, v243
	v_fma_f32 v132, v84, v178, v243
	v_fma_f32 v117, v101, v178, v243
	v_fma_f32 v133, v85, v178, v243
	v_fma_f32 v118, v102, v178, v243
	v_fma_f32 v134, v86, v178, v243
	v_fma_f32 v119, v103, v178, v243
	v_fma_f32 v135, v87, v178, v243
	v_fma_f32 v120, v104, v178, v243
	v_fma_f32 v136, v88, v178, v243
	v_fma_f32 v121, v105, v178, v243
	v_fma_f32 v137, v89, v178, v243
	v_fma_f32 v122, v106, v178, v243
	v_fma_f32 v138, v90, v178, v243
	v_fma_f32 v123, v107, v178, v243
	v_fma_f32 v139, v91, v178, v243
	v_fma_f32 v124, v108, v178, v243
	v_fma_f32 v140, v92, v178, v243
	v_fma_f32 v125, v109, v178, v243
	v_fma_f32 v141, v93, v178, v243
	v_fma_f32 v126, v110, v178, v243
	v_fma_f32 v142, v94, v178, v243
	v_fma_f32 v127, v111, v178, v243
	v_fma_f32 v143, v95, v178, v243
.Ldf_far_nofix_a:
	v_cmp_neq_f32_e32 vcc, v227, v226
	ds_read_b64_tr_b16 v[80:81], v199 offset:20480
	ds_read_b64_tr_b16 v[82:83], v210 offset:22528
	ds_read_b64_tr_b16 v[84:85], v211 offset:20480
	ds_read_b64_tr_b16 v[86:87], v212 offset:22528
	ds_read_b64_tr_b16 v[88:89], v213 offset:20480
	ds_read_b64_tr_b16 v[90:91], v214 offset:22528
	ds_read_b64_tr_b16 v[92:93], v215 offset:20480
	ds_read_b64_tr_b16 v[94:95], v216 offset:22528
	v_exp_f32_e32 v104, v112
	v_exp_f32_e32 v105, v113
	v_exp_f32_e32 v106, v114
	v_exp_f32_e32 v107, v115
	v_exp_f32_e32 v108, v116
	v_exp_f32_e32 v109, v117
	v_exp_f32_e32 v110, v118
	v_exp_f32_e32 v111, v119
	s_cbranch_vccz .Ldf_norescale_a
	v_sub_f32_e32 v246, v226, v227
	v_exp_f32_e32 v246, v246
	s_nop 0
	v_mul_f32_e32 v219, v219, v246
	v_pk_mul_f32 v[78:79], v[78:79], v[246:247] op_sel_hi:[1,0]
	v_pk_mul_f32 v[76:77], v[76:77], v[246:247] op_sel_hi:[1,0]
	v_pk_mul_f32 v[74:75], v[74:75], v[246:247] op_sel_hi:[1,0]
	v_pk_mul_f32 v[72:73], v[72:73], v[246:247] op_sel_hi:[1,0]
	v_pk_mul_f32 v[70:71], v[70:71], v[246:247] op_sel_hi:[1,0]
	v_pk_mul_f32 v[68:69], v[68:69], v[246:247] op_sel_hi:[1,0]
	v_pk_mul_f32 v[66:67], v[66:67], v[246:247] op_sel_hi:[1,0]
	v_pk_mul_f32 v[64:65], v[64:65], v[246:247] op_sel_hi:[1,0]
	v_pk_mul_f32 v[62:63], v[62:63], v[246:247] op_sel_hi:[1,0]
	v_pk_mul_f32 v[60:61], v[60:61], v[246:247] op_sel_hi:[1,0]
	v_pk_mul_f32 v[58:59], v[58:59], v[246:247] op_sel_hi:[1,0]
	v_pk_mul_f32 v[56:57], v[56:57], v[246:247] op_sel_hi:[1,0]
	v_pk_mul_f32 v[54:55], v[54:55], v[246:247] op_sel_hi:[1,0]
	v_pk_mul_f32 v[52:53], v[52:53], v[246:247] op_sel_hi:[1,0]
	v_pk_mul_f32 v[50:51], v[50:51], v[246:247] op_sel_hi:[1,0]
	v_pk_mul_f32 v[48:49], v[48:49], v[246:247] op_sel_hi:[1,0]
	v_pk_mul_f32 v[46:47], v[46:47], v[246:247] op_sel_hi:[1,0]
	v_pk_mul_f32 v[44:45], v[44:45], v[246:247] op_sel_hi:[1,0]
	v_pk_mul_f32 v[42:43], v[42:43], v[246:247] op_sel_hi:[1,0]
	v_pk_mul_f32 v[40:41], v[40:41], v[246:247] op_sel_hi:[1,0]
	v_pk_mul_f32 v[38:39], v[38:39], v[246:247] op_sel_hi:[1,0]
	v_pk_mul_f32 v[36:37], v[36:37], v[246:247] op_sel_hi:[1,0]
	v_pk_mul_f32 v[34:35], v[34:35], v[246:247] op_sel_hi:[1,0]
	v_pk_mul_f32 v[32:33], v[32:33], v[246:247] op_sel_hi:[1,0]
	v_pk_mul_f32 v[30:31], v[30:31], v[246:247] op_sel_hi:[1,0]
	v_pk_mul_f32 v[28:29], v[28:29], v[246:247] op_sel_hi:[1,0]
	v_pk_mul_f32 v[26:27], v[26:27], v[246:247] op_sel_hi:[1,0]
	v_pk_mul_f32 v[24:25], v[24:25], v[246:247] op_sel_hi:[1,0]
	v_pk_mul_f32 v[22:23], v[22:23], v[246:247] op_sel_hi:[1,0]
	v_pk_mul_f32 v[20:21], v[20:21], v[246:247] op_sel_hi:[1,0]
	v_pk_mul_f32 v[18:19], v[18:19], v[246:247] op_sel_hi:[1,0]
	v_pk_mul_f32 v[16:17], v[16:17], v[246:247] op_sel_hi:[1,0]

; #define LAS __attribute__((address_space(3)))
; #define MFMA(a, b, c) __builtin_amdgcn_mfma_f32_32x32x16_bf16((a), (b), (c), 0, 0, 0)
; template <typename F>
; DI void diff_step(lptr sK, lptr sV, int kx0, int vl0, const bf16x8 (&qf)[4], float& m, float& l, f32x16 (&O)[4],
;                   const LAS float* tb, bool far, float cfar, int lane, F&& mid) {
;     ...
;     lptr kr = sK + r * 256;
;     bf16x8 kf[8];
; #pragma unroll
;     for (int s = 0; s < 4; ++s) {
;         const int co = (kx0 ^ (2 * s)) * 16;
;         kf[2 * s] = *(const LAS bf16x8*)(kr + co);
;         kf[2 * s + 1] = *(const LAS bf16x8*)(kr + 8192 + co);
;     }
;     __builtin_amdgcn_sched_barrier(0);
;     mid();
;     __builtin_amdgcn_sched_barrier(0);
; #pragma unroll
;     for (int s = 0; s < 4; ++s) { p0 = MFMA(kf[2 * s], qf[s], p0); p1 = MFMA(kf[2 * s + 1], qf[s], p1); }
; DI void diff_item(const Params& P, char* lds, int layer, int pair, int qt, int& tab_head) {
;     ...
;     auto issue = [&](int kt, int buf) {
;         const size_t to = (size_t)(64 * kt) * PO;
; #pragma unroll
;         for (int i = 0; i < 2; ++i) {
;             glds16(kg + to + goff[i], (unsigned)__builtin_amdgcn_readfirstlane(lds0 + buf * 32768 + (2 * w + i) * 1024));
;             glds16(vg + to + goff[i], (unsigned)__builtin_amdgcn_readfirstlane(lds0 + buf * 32768 + 16384 + (2 * w + i) * 1024));
;         }
;     };
.Ldu_B:
	s_waitcnt vmcnt(0)
	s_sub_i32 s22, s50, 64
	v_cmp_le_u32_e32 vcc, s22, v200
	v_add_u32_e32 v0, 1, v220
	s_waitcnt lgkmcnt(0)
	s_barrier
	s_and_saveexec_b64 s[22:23], vcc
	s_xor_b64 s[40:41], exec, s[22:23]
	s_cbranch_execz .LBB0_263_b
	v_add_u32_e32 v220, 1, v220
	v_cmp_gt_u32_e32 vcc, s49, v220
	v_cmp_gt_i32_e64 s[100:101], s42, v217
	ds_read_b128 v[248:251], v14 offset:32768
	ds_read_b128 v[252:255], v14 offset:40960
	ds_read_b128 v[120:123], v15 offset:32768
	ds_read_b128 v[6:9], v15 offset:40960
	ds_read_b128 v[116:119], v221 offset:32768
	ds_read_b128 v[2:5], v221 offset:40960
	ds_read_b128 v[10:13], v222 offset:32768
	ds_read_b128 v[112:115], v222 offset:40960
	s_and_saveexec_b64 s[22:23], vcc
	s_cbranch_execz .LBB0_256_b
	s_mov_b32 s72, s63
	s_mov_b32 m0, s72
	s_nop 0
	global_load_lds_dwordx4 v170, s[64:65]
	s_add_u32 s72, s63, 0x4000
	s_mov_b32 m0, s72
	s_nop 0
	global_load_lds_dwordx4 v170, s[70:71]
	s_add_u32 s72, s63, 0x400
	s_mov_b32 m0, s72
	s_nop 0
	global_load_lds_dwordx4 v172, s[64:65]
	s_add_u32 s72, s63, 0x4400
	s_mov_b32 m0, s72
	s_nop 0
	global_load_lds_dwordx4 v172, s[70:71]
	s_add_u32 s64, s64, 0xe0000
	s_addc_u32 s65, s65, 0
	s_add_u32 s70, s70, 0xe0000
	s_addc_u32 s71, s71, 0
.LBB0_256_b:
	s_or_b64 exec, exec, s[22:23]
	s_cmp_eq_u64 s[100:101], 0
	s_cbranch_scc1 .Lqk_far_b
	ds_read2_b32 v[96:97], v218 offset0:59 offset1:58
	ds_read2_b32 v[98:99], v218 offset0:57 offset1:56
	ds_read2_b32 v[100:101], v218 offset0:51 offset1:50
	ds_read2_b32 v[102:103], v218 offset0:49 offset1:48
	ds_read2_b32 v[104:105], v218 offset0:43 offset1:42
	ds_read2_b32 v[106:107], v218 offset0:41 offset1:40
	ds_read2_b32 v[108:109], v218 offset0:35 offset1:34
	ds_read2_b32 v[110:111], v218 offset0:33 offset1:32
	ds_read2_b32 v[80:81], v218 offset0:27 offset1:26
	ds_read2_b32 v[82:83], v218 offset0:25 offset1:24
	ds_read2_b32 v[84:85], v218 offset0:19 offset1:18
	ds_read2_b32 v[86:87], v218 offset0:17 offset1:16
	ds_read2_b32 v[88:89], v218 offset0:11 offset1:10
	ds_read2_b32 v[90:91], v218 offset0:9 offset1:8
	ds_read2_b32 v[92:93], v218 offset0:3 offset1:2
	ds_read2_b32 v[94:95], v218 offset0:1 offset1:0
	v_mov_b32_e32 v242, 0
	s_waitcnt lgkmcnt(0)
	v_mfma_f32_32x32x16_bf16 v[96:111], v[248:251], v[144:147], v[96:111]
	v_mfma_f32_32x32x16_bf16 v[80:95], v[252:255], v[144:147], v[80:95]
	s_branch .Lqk_join_b

.Lqk_join_b:
	s_waitcnt lgkmcnt(5)
	v_mfma_f32_32x32x16_bf16 v[96:111], v[120:123], v[148:151], v[96:111]
	s_waitcnt lgkmcnt(4)
	v_mfma_f32_32x32x16_bf16 v[80:95], v[6:9], v[148:151], v[80:95]
	s_waitcnt lgkmcnt(3)
	v_mfma_f32_32x32x16_bf16 v[96:111], v[116:119], v[152:155], v[96:111]
	s_waitcnt lgkmcnt(2)
	v_mfma_f32_32x32x16_bf16 v[80:95], v[2:5], v[152:155], v[80:95]
	ds_read_b64_tr_b16 v[2:3], v199 offset:49152
	ds_read_b64_tr_b16 v[4:5], v210 offset:51200
	ds_read_b64_tr_b16 v[6:7], v211 offset:49152
	ds_read_b64_tr_b16 v[8:9], v212 offset:51200
	s_waitcnt lgkmcnt(5)
	v_mfma_f32_32x32x16_bf16 v[96:111], v[10:13], v[156:159], v[96:111]
	ds_read_b64_tr_b16 v[10:11], v213 offset:49152
	ds_read_b64_tr_b16 v[12:13], v214 offset:51200
	ds_read_b64_tr_b16 v[160:161], v215 offset:49152
	ds_read_b64_tr_b16 v[162:163], v216 offset:51200
	s_waitcnt lgkmcnt(8)
	v_mfma_f32_32x32x16_bf16 v[80:95], v[112:115], v[156:159], v[80:95]
	s_nop 7
	s_nop 7
	s_nop 3
	v_sub_f32_e32 v243, v242, v226
	v_max3_f32 v244, v96, v97, v80
	v_fma_f32 v112, v96, v178, v243
	v_fma_f32 v128, v80, v178, v243
	v_max3_f32 v245, v98, v99, v81
	v_fma_f32 v113, v97, v178, v243
	v_fma_f32 v129, v81, v178, v243
	v_max3_f32 v244, v244, v82, v83
	v_fma_f32 v114, v98, v178, v243
	v_fma_f32 v130, v82, v178, v243
	v_max3_f32 v245, v245, v102, v103
	v_fma_f32 v115, v99, v178, v243
	v_fma_f32 v131, v83, v178, v243
	v_max3_f32 v244, v244, v100, v101
	v_fma_f32 v116, v100, v178, v243
	v_fma_f32 v132, v84, v178, v243
	v_max3_f32 v245, v245, v86, v87
	v_fma_f32 v117, v101, v178, v243
	v_fma_f32 v133, v85, v178, v243
	v_max3_f32 v244, v244, v84, v85
	v_fma_f32 v118, v102, v178, v243
	v_fma_f32 v134, v86, v178, v243
	v_max3_f32 v245, v245, v106, v107
	v_fma_f32 v119, v103, v178, v243
	v_fma_f32 v135, v87, v178, v243
	v_max3_f32 v244, v244, v104, v105
	v_fma_f32 v120, v104, v178, v243
	v_fma_f32 v136, v88, v178, v243
	v_max3_f32 v245, v245, v90, v91
	v_fma_f32 v121, v105, v178, v243
	v_fma_f32 v137, v89, v178, v243
	v_max3_f32 v244, v244, v88, v89
	v_fma_f32 v122, v106, v178, v243
	v_fma_f32 v138, v90, v178, v243
	v_max3_f32 v245, v245, v110, v111
	v_fma_f32 v123, v107, v178, v243
	v_fma_f32 v139, v91, v178, v243
	v_max3_f32 v244, v244, v108, v109
	v_fma_f32 v124, v108, v178, v243
	v_fma_f32 v140, v92, v178, v243
	v_max3_f32 v245, v245, v94, v95
	v_fma_f32 v125, v109, v178, v243
	v_fma_f32 v141, v93, v178, v243
	v_max3_f32 v244, v244, v92, v93
	v_fma_f32 v126, v110, v178, v243
	v_fma_f32 v142, v94, v178, v243
	v_fma_f32 v127, v111, v178, v243
	v_fma_f32 v143, v95, v178, v243
	v_max_f32_e32 v244, v244, v245
	v_mov_b32_e32 v245, v244
	s_nop 1
	v_permlane32_swap_b32_e32 v244, v245
	v_max_f32_e32 v244, v244, v245
	v_fmamk_f32 v244, v244, 0x3e38aa3b, v242
	v_sub_f32_e32 v245, v244, v226
	v_cmp_lt_f32_e32 vcc, s45, v245
	v_max_f32_e32 v244, v226, v244
	s_nop 0
	v_cndmask_b32_e32 v227, v226, v244, vcc
	s_nop 2
	s_cbranch_vccz .Ldf_far_nofix_b
	v_sub_f32_e32 v243, v242, v227
	v_fma_f32 v112, v96, v178, v243
	v_fma_f32 v128, v80, v178, v243
	v_fma_f32 v113, v97, v178, v243
	v_fma_f32 v129, v81, v178, v243
	v_fma_f32 v114, v98, v178, v243
	v_fma_f32 v130, v82, v178, v243
	v_fma_f32 v115, v99, v178, v243
	v_fma_f32 v131, v83, v178, v243
	v_fma_f32 v116, v100, v178, v243
	v_fma_f32 v132, v84, v178, v243
	v_fma_f32 v117, v101, v178, v243
	v_fma_f32 v133, v85, v178, v243
	v_fma_f32 v118, v102, v178, v243
	v_fma_f32 v134, v86, v178, v243
	v_fma_f32 v119, v103, v178, v243
	v_fma_f32 v135, v87, v178, v243
	v_fma_f32 v120, v104, v178, v243
	v_fma_f32 v136, v88, v178, v243
	v_fma_f32 v121, v105, v178, v243
	v_fma_f32 v137, v89, v178, v243
	v_fma_f32 v122, v106, v178, v243
	v_fma_f32 v138, v90, v178, v243
	v_fma_f32 v123, v107, v178, v243
	v_fma_f32 v139, v91, v178, v243
	v_fma_f32 v124, v108, v178, v243
	v_fma_f32 v140, v92, v178, v243
	v_fma_f32 v125, v109, v178, v243
	v_fma_f32 v141, v93, v178, v243
	v_fma_f32 v126, v110, v178, v243
	v_fma_f32 v142, v94, v178, v243
	v_fma_f32 v127, v111, v178, v243
	v_fma_f32 v143, v95, v178, v243
.Ldf_far_nofix_b:
	v_cmp_neq_f32_e32 vcc, v227, v226
	ds_read_b64_tr_b16 v[80:81], v199 offset:53248
	ds_read_b64_tr_b16 v[82:83], v210 offset:55296
	ds_read_b64_tr_b16 v[84:85], v211 offset:53248
	ds_read_b64_tr_b16 v[86:87], v212 offset:55296
	ds_read_b64_tr_b16 v[88:89], v213 offset:53248
	ds_read_b64_tr_b16 v[90:91], v214 offset:55296
	ds_read_b64_tr_b16 v[92:93], v215 offset:53248
	ds_read_b64_tr_b16 v[94:95], v216 offset:55296
	v_exp_f32_e32 v104, v112
	v_exp_f32_e32 v105, v113
	v_exp_f32_e32 v106, v114
	v_exp_f32_e32 v107, v115
	v_exp_f32_e32 v108, v116
	v_exp_f32_e32 v109, v117
	v_exp_f32_e32 v110, v118
	v_exp_f32_e32 v111, v119
	s_cbranch_vccz .Ldf_norescale_b
	v_sub_f32_e32 v246, v226, v227
	v_exp_f32_e32 v246, v246
	s_nop 0
	v_mul_f32_e32 v219, v219, v246
	v_pk_mul_f32 v[78:79], v[78:79], v[246:247] op_sel_hi:[1,0]
	v_pk_mul_f32 v[76:77], v[76:77], v[246:247] op_sel_hi:[1,0]
	v_pk_mul_f32 v[74:75], v[74:75], v[246:247] op_sel_hi:[1,0]
	v_pk_mul_f32 v[72:73], v[72:73], v[246:247] op_sel_hi:[1,0]
	v_pk_mul_f32 v[70:71], v[70:71], v[246:247] op_sel_hi:[1,0]
	v_pk_mul_f32 v[68:69], v[68:69], v[246:247] op_sel_hi:[1,0]
	v_pk_mul_f32 v[66:67], v[66:67], v[246:247] op_sel_hi:[1,0]
	v_pk_mul_f32 v[64:65], v[64:65], v[246:247] op_sel_hi:[1,0]
	v_pk_mul_f32 v[62:63], v[62:63], v[246:247] op_sel_hi:[1,0]
	v_pk_mul_f32 v[60:61], v[60:61], v[246:247] op_sel_hi:[1,0]
	v_pk_mul_f32 v[58:59], v[58:59], v[246:247] op_sel_hi:[1,0]
	v_pk_mul_f32 v[56:57], v[56:57], v[246:247] op_sel_hi:[1,0]
	v_pk_mul_f32 v[54:55], v[54:55], v[246:247] op_sel_hi:[1,0]
	v_pk_mul_f32 v[52:53], v[52:53], v[246:247] op_sel_hi:[1,0]
	v_pk_mul_f32 v[50:51], v[50:51], v[246:247] op_sel_hi:[1,0]
	v_pk_mul_f32 v[48:49], v[48:49], v[246:247] op_sel_hi:[1,0]
	v_pk_mul_f32 v[46:47], v[46:47], v[246:247] op_sel_hi:[1,0]
	v_pk_mul_f32 v[44:45], v[44:45], v[246:247] op_sel_hi:[1,0]
	v_pk_mul_f32 v[42:43], v[42:43], v[246:247] op_sel_hi:[1,0]
	v_pk_mul_f32 v[40:41], v[40:41], v[246:247] op_sel_hi:[1,0]
	v_pk_mul_f32 v[38:39], v[38:39], v[246:247] op_sel_hi:[1,0]
	v_pk_mul_f32 v[36:37], v[36:37], v[246:247] op_sel_hi:[1,0]
	v_pk_mul_f32 v[34:35], v[34:35], v[246:247] op_sel_hi:[1,0]
	v_pk_mul_f32 v[32:33], v[32:33], v[246:247] op_sel_hi:[1,0]
	v_pk_mul_f32 v[30:31], v[30:31], v[246:247] op_sel_hi:[1,0]
	v_pk_mul_f32 v[28:29], v[28:29], v[246:247] op_sel_hi:[1,0]
	v_pk_mul_f32 v[26:27], v[26:27], v[246:247] op_sel_hi:[1,0]
	v_pk_mul_f32 v[24:25], v[24:25], v[246:247] op_sel_hi:[1,0]
	v_pk_mul_f32 v[22:23], v[22:23], v[246:247] op_sel_hi:[1,0]
	v_pk_mul_f32 v[20:21], v[20:21], v[246:247] op_sel_hi:[1,0]
	v_pk_mul_f32 v[18:19], v[18:19], v[246:247] op_sel_hi:[1,0]
	v_pk_mul_f32 v[16:17], v[16:17], v[246:247] op_sel_hi:[1,0]
